# speedup vs baseline: 1.0043x; 1.0043x over previous
; __device__ __forceinline__ float bf2f(bfr h) { return __uint_as_float(((unsigned)h) << 16); }
; __device__ __forceinline__ void shw_phase(const Params& p) {
;     ...
;     float wv[16];
; #pragma unroll
;     for (int h = 0; h < 2; h++) {
;       bf16x8 w8 = *(const bf16x8*)(W + (size_t)n * D + h * 512 + lane * 8);
; #pragma unroll
;       for (int i = 0; i < 8; i++) wv[h * 8 + i] = bf2f((bfr)w8[i]);
;     }
; #pragma unroll
;     for (int b = 0; b < 9; b++) {
;       float a = 0.f;
; #pragma unroll
;       for (int i = 0; i < 16; i++) a += sh[b][i] * wv[i];
; #pragma unroll
;       for (int m = 32; m >= 1; m >>= 1) a += __shfl_xor(a, m);
;       if (lane == 0) p.shW[off + b * N + n] = a;
;     }
.LBB0_147:
	s_or_b64 exec, exec, s[18:19]
	v_ashrrev_i32_e32 v149, 31, v148
	v_lshlrev_b64 v[152:153], 11, v[148:149]
	v_lshl_add_u64 v[150:151], v[150:151], 0, v[152:153]
	v_lshl_add_u64 v[150:151], v[150:151], 0, v[144:145]
	global_load_dwordx4 v[170:173], v[150:151], off
	global_load_dwordx4 v[178:181], v[150:151], off offset:1024
	v_add_u32_e32 v148, v148, v166
	s_waitcnt vmcnt(1)
	v_lshlrev_b32_e32 v168, 16, v170
	v_and_b32_e32 v167, 0xffff0000, v170
	v_fma_f32 v149, v4, v168, 0
	v_lshlrev_b32_e32 v155, 16, v171
	v_fmac_f32_e32 v149, v5, v167
	v_and_b32_e32 v154, 0xffff0000, v171
	v_fmac_f32_e32 v149, v6, v155
	v_lshlrev_b32_e32 v153, 16, v172
	v_fmac_f32_e32 v149, v7, v154
	v_and_b32_e32 v152, 0xffff0000, v172
	v_fmac_f32_e32 v149, v0, v153
	v_lshlrev_b32_e32 v151, 16, v173
	v_fmac_f32_e32 v149, v1, v152
	v_and_b32_e32 v150, 0xffff0000, v173
	v_fmac_f32_e32 v149, v2, v151
	s_waitcnt vmcnt(0)
	v_lshlrev_b32_e32 v176, 16, v178
	v_fmac_f32_e32 v149, v3, v150
	v_and_b32_e32 v175, 0xffff0000, v178
	v_fmac_f32_e32 v149, v12, v176
	v_lshlrev_b32_e32 v174, 16, v179
	v_fmac_f32_e32 v149, v13, v175
	v_and_b32_e32 v173, 0xffff0000, v179
	v_fmac_f32_e32 v149, v14, v174
	v_lshlrev_b32_e32 v172, 16, v180
	v_fmac_f32_e32 v149, v15, v173
	v_and_b32_e32 v171, 0xffff0000, v180
	v_fmac_f32_e32 v149, v8, v172
	v_lshlrev_b32_e32 v170, 16, v181
	v_fmac_f32_e32 v149, v9, v171
	v_and_b32_e32 v169, 0xffff0000, v181
	v_fmac_f32_e32 v149, v10, v170
	v_fmac_f32_e32 v149, v11, v169
	v_mov_b32_e32 v182, v149
	v_fma_f32 v183, v20, v168, 0
	v_fmac_f32_e32 v183, v21, v167
	v_fmac_f32_e32 v183, v22, v155
	v_fmac_f32_e32 v183, v23, v154
	v_fmac_f32_e32 v183, v16, v153
	v_fmac_f32_e32 v183, v17, v152
	v_fmac_f32_e32 v183, v18, v151
	v_fmac_f32_e32 v183, v19, v150
	v_fmac_f32_e32 v183, v28, v176
	v_fmac_f32_e32 v183, v29, v175
	v_fmac_f32_e32 v183, v30, v174
	v_fmac_f32_e32 v183, v31, v173
	v_fmac_f32_e32 v183, v24, v172
	v_fmac_f32_e32 v183, v25, v171
	v_fmac_f32_e32 v183, v26, v170
	v_fmac_f32_e32 v183, v27, v169
	v_fma_f32 v184, v36, v168, 0
	v_fmac_f32_e32 v184, v37, v167
	v_fmac_f32_e32 v184, v38, v155
	v_fmac_f32_e32 v184, v39, v154
	v_fmac_f32_e32 v184, v32, v153
	v_fmac_f32_e32 v184, v33, v152
	v_fmac_f32_e32 v184, v34, v151
	v_fmac_f32_e32 v184, v35, v150
	v_fmac_f32_e32 v184, v44, v176
	v_fmac_f32_e32 v184, v45, v175
	v_fmac_f32_e32 v184, v46, v174
	v_fmac_f32_e32 v184, v47, v173
	v_fmac_f32_e32 v184, v40, v172
	v_fmac_f32_e32 v184, v41, v171
	v_fmac_f32_e32 v184, v42, v170
	v_fmac_f32_e32 v184, v43, v169
	v_fma_f32 v185, v52, v168, 0
	v_fmac_f32_e32 v185, v53, v167
	v_fmac_f32_e32 v185, v54, v155
	v_fmac_f32_e32 v185, v55, v154
	v_fmac_f32_e32 v185, v48, v153
	v_fmac_f32_e32 v185, v49, v152
	v_fmac_f32_e32 v185, v50, v151
	v_fmac_f32_e32 v185, v51, v150
	v_fmac_f32_e32 v185, v60, v176
	v_fmac_f32_e32 v185, v61, v175
	v_fmac_f32_e32 v185, v62, v174
	v_fmac_f32_e32 v185, v63, v173
	v_fmac_f32_e32 v185, v56, v172
	v_fmac_f32_e32 v185, v57, v171
	v_fmac_f32_e32 v185, v58, v170
	v_fmac_f32_e32 v185, v59, v169
	v_fma_f32 v186, v68, v168, 0
	v_fmac_f32_e32 v186, v69, v167
	v_fmac_f32_e32 v186, v70, v155
	v_fmac_f32_e32 v186, v71, v154
	v_fmac_f32_e32 v186, v64, v153
	v_fmac_f32_e32 v186, v65, v152
	v_fmac_f32_e32 v186, v66, v151
	v_fmac_f32_e32 v186, v67, v150
	v_fmac_f32_e32 v186, v76, v176
	v_fmac_f32_e32 v186, v77, v175
	v_fmac_f32_e32 v186, v78, v174
	v_fmac_f32_e32 v186, v79, v173
	v_fmac_f32_e32 v186, v72, v172
	v_fmac_f32_e32 v186, v73, v171
	v_fmac_f32_e32 v186, v74, v170
	v_fmac_f32_e32 v186, v75, v169
	v_fma_f32 v187, v84, v168, 0
	v_fmac_f32_e32 v187, v85, v167
	v_fmac_f32_e32 v187, v86, v155
	v_fmac_f32_e32 v187, v87, v154
	v_fmac_f32_e32 v187, v80, v153
	v_fmac_f32_e32 v187, v81, v152
	v_fmac_f32_e32 v187, v82, v151
	v_fmac_f32_e32 v187, v83, v150
	v_fmac_f32_e32 v187, v92, v176
	v_fmac_f32_e32 v187, v93, v175
	v_fmac_f32_e32 v187, v94, v174
	v_fmac_f32_e32 v187, v95, v173
	v_fmac_f32_e32 v187, v88, v172
	v_fmac_f32_e32 v187, v89, v171
	v_fmac_f32_e32 v187, v90, v170
	v_fmac_f32_e32 v187, v91, v169
	v_fma_f32 v188, v104, v168, 0
	v_fmac_f32_e32 v188, v105, v167
	v_fmac_f32_e32 v188, v106, v155
	v_fmac_f32_e32 v188, v107, v154
	v_fmac_f32_e32 v188, v100, v153
	v_fmac_f32_e32 v188, v101, v152
	v_fmac_f32_e32 v188, v102, v151
	v_fmac_f32_e32 v188, v103, v150
	v_fmac_f32_e32 v188, v112, v176
	v_fmac_f32_e32 v188, v113, v175
	v_fmac_f32_e32 v188, v114, v174
	v_fmac_f32_e32 v188, v115, v173
	v_fmac_f32_e32 v188, v108, v172
	v_fmac_f32_e32 v188, v109, v171
	v_fmac_f32_e32 v188, v110, v170
	v_fmac_f32_e32 v188, v111, v169
	v_fma_f32 v189, v120, v168, 0
	v_fmac_f32_e32 v189, v121, v167
	v_fmac_f32_e32 v189, v122, v155
	v_fmac_f32_e32 v189, v123, v154
	v_fmac_f32_e32 v189, v116, v153
	v_fmac_f32_e32 v189, v117, v152
	v_fmac_f32_e32 v189, v118, v151
	v_fmac_f32_e32 v189, v119, v150
	v_fmac_f32_e32 v189, v124, v176
	v_fmac_f32_e32 v189, v125, v175
	v_fmac_f32_e32 v189, v126, v174
	v_fmac_f32_e32 v189, v127, v173
	v_fmac_f32_e32 v189, v96, v172
	v_fmac_f32_e32 v189, v97, v171
	v_fmac_f32_e32 v189, v98, v170
	v_fmac_f32_e32 v189, v99, v169
	v_fma_f32 v190, v128, v168, 0
	v_fmac_f32_e32 v190, v129, v167
	v_fmac_f32_e32 v190, v130, v155
	v_fmac_f32_e32 v190, v131, v154
	v_fmac_f32_e32 v190, v132, v153
	v_fmac_f32_e32 v190, v133, v152
	v_fmac_f32_e32 v190, v134, v151
	v_fmac_f32_e32 v190, v135, v150
	v_fmac_f32_e32 v190, v136, v176
	v_fmac_f32_e32 v190, v137, v175
	v_fmac_f32_e32 v190, v138, v174
	v_fmac_f32_e32 v190, v139, v173
	v_fmac_f32_e32 v190, v140, v172
	v_fmac_f32_e32 v190, v141, v171
	v_fmac_f32_e32 v190, v142, v170
	v_fmac_f32_e32 v190, v143, v169
	ds_bpermute_b32 v192, v158, v182
	ds_bpermute_b32 v193, v158, v183
	ds_bpermute_b32 v194, v158, v184
	ds_bpermute_b32 v195, v158, v185
	ds_bpermute_b32 v196, v158, v186
	ds_bpermute_b32 v197, v158, v187
	ds_bpermute_b32 v198, v158, v188
	ds_bpermute_b32 v199, v158, v189
	ds_bpermute_b32 v200, v158, v190
	s_waitcnt lgkmcnt(0)
; __device__ __forceinline__ void shw_phase(const Params& p) {
;     ...
; #pragma unroll
;     for (int b = 0; b < 9; b++) {
;       float a = 0.f;
; #pragma unroll
;       for (int i = 0; i < 16; i++) a += sh[b][i] * wv[i];
; #pragma unroll
;       for (int m = 32; m >= 1; m >>= 1) a += __shfl_xor(a, m);
;       if (lane == 0) p.shW[off + b * N + n] = a;
;     }
	v_add_f32_e32 v182, v182, v192
	v_add_f32_e32 v183, v183, v193
	v_add_f32_e32 v184, v184, v194
	v_add_f32_e32 v185, v185, v195
	v_add_f32_e32 v186, v186, v196
	v_add_f32_e32 v187, v187, v197
	v_add_f32_e32 v188, v188, v198
	v_add_f32_e32 v189, v189, v199
	v_add_f32_e32 v190, v190, v200
	ds_bpermute_b32 v192, v159, v182
	ds_bpermute_b32 v193, v159, v183
	ds_bpermute_b32 v194, v159, v184
	ds_bpermute_b32 v195, v159, v185
	ds_bpermute_b32 v196, v159, v186
	ds_bpermute_b32 v197, v159, v187
	ds_bpermute_b32 v198, v159, v188
	ds_bpermute_b32 v199, v159, v189
	ds_bpermute_b32 v200, v159, v190
	s_waitcnt lgkmcnt(0)
	v_add_f32_e32 v182, v182, v192
	v_add_f32_e32 v183, v183, v193
	v_add_f32_e32 v184, v184, v194
	v_add_f32_e32 v185, v185, v195
	v_add_f32_e32 v186, v186, v196
	v_add_f32_e32 v187, v187, v197
	v_add_f32_e32 v188, v188, v198
	v_add_f32_e32 v189, v189, v199
	v_add_f32_e32 v190, v190, v200
	ds_bpermute_b32 v192, v160, v182
	ds_bpermute_b32 v193, v160, v183
	ds_bpermute_b32 v194, v160, v184
	ds_bpermute_b32 v195, v160, v185
	ds_bpermute_b32 v196, v160, v186
	ds_bpermute_b32 v197, v160, v187
	ds_bpermute_b32 v198, v160, v188
	ds_bpermute_b32 v199, v160, v189
	ds_bpermute_b32 v200, v160, v190
	s_waitcnt lgkmcnt(0)
	v_add_f32_e32 v182, v182, v192
	v_add_f32_e32 v183, v183, v193
	v_add_f32_e32 v184, v184, v194
	v_add_f32_e32 v185, v185, v195
	v_add_f32_e32 v186, v186, v196
	v_add_f32_e32 v187, v187, v197
	v_add_f32_e32 v188, v188, v198
	v_add_f32_e32 v189, v189, v199
	v_add_f32_e32 v190, v190, v200
	ds_bpermute_b32 v192, v161, v182
	ds_bpermute_b32 v193, v161, v183
	ds_bpermute_b32 v194, v161, v184
	ds_bpermute_b32 v195, v161, v185
	ds_bpermute_b32 v196, v161, v186
	ds_bpermute_b32 v197, v161, v187
	ds_bpermute_b32 v198, v161, v188
	ds_bpermute_b32 v199, v161, v189
	ds_bpermute_b32 v200, v161, v190
	s_waitcnt lgkmcnt(0)
	v_add_f32_e32 v182, v182, v192
	v_add_f32_e32 v183, v183, v193
	v_add_f32_e32 v184, v184, v194
	v_add_f32_e32 v185, v185, v195
	v_add_f32_e32 v186, v186, v196
	v_add_f32_e32 v187, v187, v197
	v_add_f32_e32 v188, v188, v198
	v_add_f32_e32 v189, v189, v199
	v_add_f32_e32 v190, v190, v200
	ds_bpermute_b32 v192, v162, v182
	ds_bpermute_b32 v193, v162, v183
	ds_bpermute_b32 v194, v162, v184
	ds_bpermute_b32 v195, v162, v185
	ds_bpermute_b32 v196, v162, v186
	ds_bpermute_b32 v197, v162, v187
	ds_bpermute_b32 v198, v162, v188
	ds_bpermute_b32 v199, v162, v189
	ds_bpermute_b32 v200, v162, v190
	s_waitcnt lgkmcnt(0)
	v_add_f32_e32 v182, v182, v192
	v_add_f32_e32 v183, v183, v193
	v_add_f32_e32 v184, v184, v194
	v_add_f32_e32 v185, v185, v195
	v_add_f32_e32 v186, v186, v196
	v_add_f32_e32 v187, v187, v197
	v_add_f32_e32 v188, v188, v198
	v_add_f32_e32 v189, v189, v199
	v_add_f32_e32 v190, v190, v200
	ds_bpermute_b32 v192, v163, v182
	ds_bpermute_b32 v193, v163, v183
	ds_bpermute_b32 v194, v163, v184
	ds_bpermute_b32 v195, v163, v185
	ds_bpermute_b32 v196, v163, v186
	ds_bpermute_b32 v197, v163, v187
	ds_bpermute_b32 v198, v163, v188
	ds_bpermute_b32 v199, v163, v189
	ds_bpermute_b32 v200, v163, v190
	s_waitcnt lgkmcnt(0)
	v_add_f32_e32 v182, v182, v192
	v_add_f32_e32 v183, v183, v193
	v_add_f32_e32 v184, v184, v194
	v_add_f32_e32 v185, v185, v195
	v_add_f32_e32 v186, v186, v196
	v_add_f32_e32 v187, v187, v197
	v_add_f32_e32 v188, v188, v198
	v_add_f32_e32 v189, v189, v199
	v_add_f32_e32 v190, v190, v200
	s_and_saveexec_b64 s[0:1], vcc
	v_mov_b32_e32 v202, v148
	v_ashrrev_i32_e32 v203, 31, v202
	v_lshl_add_u64 v[202:203], v[202:203], 2, s[88:89]
	global_store_dword v[202:203], v182, off
	v_mad_u32_u24 v202, v165, 1, v148
	v_ashrrev_i32_e32 v203, 31, v202
	v_lshl_add_u64 v[202:203], v[202:203], 2, s[88:89]
	global_store_dword v[202:203], v183, off
	v_mad_u32_u24 v202, v165, 2, v148
	v_ashrrev_i32_e32 v203, 31, v202
	v_lshl_add_u64 v[202:203], v[202:203], 2, s[88:89]
	global_store_dword v[202:203], v184, off
	v_mad_u32_u24 v202, v165, 3, v148
	v_ashrrev_i32_e32 v203, 31, v202
	v_lshl_add_u64 v[202:203], v[202:203], 2, s[88:89]
	global_store_dword v[202:203], v185, off
	v_mad_u32_u24 v202, v165, 4, v148
	v_ashrrev_i32_e32 v203, 31, v202
	v_lshl_add_u64 v[202:203], v[202:203], 2, s[88:89]
	global_store_dword v[202:203], v186, off
	v_mad_u32_u24 v202, v165, 5, v148
	v_ashrrev_i32_e32 v203, 31, v202
	v_lshl_add_u64 v[202:203], v[202:203], 2, s[88:89]
	global_store_dword v[202:203], v187, off
	v_mad_u32_u24 v202, v165, 6, v148
	v_ashrrev_i32_e32 v203, 31, v202
	v_lshl_add_u64 v[202:203], v[202:203], 2, s[88:89]
	global_store_dword v[202:203], v188, off
	v_mad_u32_u24 v202, v165, 7, v148
	v_ashrrev_i32_e32 v203, 31, v202
	v_lshl_add_u64 v[202:203], v[202:203], 2, s[88:89]
	global_store_dword v[202:203], v189, off
	v_mad_u32_u24 v202, v165, 8, v148
	v_ashrrev_i32_e32 v203, 31, v202
	v_lshl_add_u64 v[202:203], v[202:203], 2, s[88:89]
	global_store_dword v[202:203], v190, off
	s_branch .LBB0_130
